# F2 input loader remapped so each 16-byte load instruction reads whole 128-byte lines (lane lp takes chunks lp, lp+8, lp+16, lp+24 of the half row); LDS tile writes follow the same map
# speedup vs baseline: 1.0120x; 1.0120x over previous
.LBB0_307:
	s_lshl_b32 s5, s2, 5
	v_lshrrev_b32_e32 v1, 3, v0
	s_and_b32 s0, s5, 0xffffffc0
	s_waitcnt vmcnt(0)
	v_or_b32_e32 v2, s0, v1
	v_ashrrev_i32_e32 v3, 31, v2
	s_lshl_b32 s0, s2, 8
	v_lshlrev_b64 v[2:3], 9, v[2:3]
	s_and_b32 s0, s0, 0x100
	v_lshlrev_b32_e32 v74, 3, v75
	v_or3_b32 v2, v2, s0, v74
	v_lshlrev_b64 v[2:3], 1, v[2:3]
	v_lshl_add_u64 v[34:35], s[14:15], 0, v[2:3]
	v_lshl_add_u64 v[36:37], s[12:13], 0, v[2:3]
	global_load_dwordx4 v[2:5], v[34:35], off offset:384
	global_load_dwordx4 v[6:9], v[34:35], off offset:256
	global_load_dwordx4 v[10:13], v[34:35], off offset:128
	global_load_dwordx4 v[14:17], v[34:35], off
	global_load_dwordx4 v[18:21], v[36:37], off offset:384
	global_load_dwordx4 v[22:25], v[36:37], off offset:256
	global_load_dwordx4 v[26:29], v[36:37], off offset:128
	global_load_dwordx4 v[30:33], v[36:37], off
	v_lshrrev_b32_e32 v39, 1, v0
	s_and_b32 s4, s78, 0xffffffc0
	v_and_b32_e32 v34, 15, v0
	v_bfe_u32 v36, v0, 2, 2
	v_and_b32_e32 v39, 24, v39
	s_add_i32 s4, s4, 0
	s_movk_i32 s0, 0x210
	v_lshlrev_b32_e32 v90, 6, v34
	v_or_b32_e32 v36, v39, v36
	v_mul_u32_u24_e32 v42, 0x110, v34
	v_mov_b32_e32 v34, s4
	v_mad_u32_u24 v37, v1, s0, 0
	s_lshr_b32 s8, s78, 7
	v_mad_u32_u24 v36, v36, s0, v34
	s_lshl_b32 s0, s33, 6
	s_add_i32 s8, s8, 32
	v_and_b32_e32 v41, 48, v0
	s_add_i32 s6, 0, 0x10800
	s_and_b32 s0, s0, 64
	v_lshlrev_b32_e32 v40, 4, v0
	v_add_u32_e32 v41, s6, v41
	s_add_u32 s6, s20, s0
	v_mov_b32_e32 v35, 0
	v_lshlrev_b32_e32 v38, 4, v75
	v_and_b32_e32 v40, 48, v40
	s_addc_u32 s7, s21, 0
	v_lshlrev_b32_e32 v34, 1, v39
	s_mov_b32 s1, 0
	v_lshl_or_b32 v91, s33, 5, v39
	v_lshl_add_u64 v[76:77], s[6:7], 0, v[34:35]
	s_lshl_b32 s9, s3, 5
	v_add_u32_e32 v92, v37, v38
	v_add_u32_e32 v93, v36, v40
	v_add_u32_e32 v94, v41, v42
	s_mov_b32 s4, 0x3ab504f3
	s_mov_b32 s10, s5
	s_mov_b32 s11, s2
	s_mov_b64 s[84:85], 0x20000
	s_and_b32 s80, s2, 1
	s_lshl_b32 s80, s80, 2
	s_add_i32 s80, s8, s80
	s_mov_b32 s81, 0
	s_lshl_b64 s[80:81], s[80:81], 23
	s_lshl_b32 s82, s2, 5
	s_and_b32 s82, s82, 0xfffff000
	s_lshr_b32 s83, s2, 1
	s_and_b32 s83, s83, 63
	s_or_b32 s82, s82, s83
	v_or_b32_e32 v116, s82, v90
	v_lshlrev_b32_e32 v116, 7, v116
	v_mov_b32_e32 v117, 0
	v_lshl_add_u64 v[116:117], v[76:77], 0, v[116:117]
	v_lshl_add_u64 v[116:117], v[116:117], 0, s[80:81]
	global_load_dwordx4 v[120:123], v[116:117], off
	v_lshl_add_u64 v[116:117], v[116:117], 0, s[84:85]
	global_load_dwordx4 v[124:127], v[116:117], off
	v_lshl_add_u64 v[116:117], v[116:117], 0, s[84:85]
	global_load_dwordx4 v[128:131], v[116:117], off
	v_lshl_add_u64 v[116:117], v[116:117], 0, s[84:85]
	global_load_dwordx4 v[132:135], v[116:117], off
	s_waitcnt vmcnt(0)
.LBB0_308:
	s_and_b32 s20, s11, 1
	s_lshl_b32 s0, s20, 2
	s_add_i32 s0, s8, s0
	s_lshl_b64 s[6:7], s[0:1], 23
	s_and_b32 s0, s10, 0xfffff000
	s_lshr_b32 s21, s11, 1
	s_waitcnt lgkmcnt(0)
	s_barrier
	s_waitcnt vmcnt(4)
	ds_write_b128 v92, v[14:17]
	ds_write_b128 v92, v[30:33] offset:33792
	ds_write_b128 v92, v[10:13] offset:128
	ds_write_b128 v92, v[26:29] offset:33920
	ds_write_b128 v92, v[6:9] offset:256
	ds_write_b128 v92, v[22:25] offset:34048
	ds_write_b128 v92, v[2:5] offset:384
	ds_write_b128 v92, v[18:21] offset:34176
	v_or_b32_e32 v2, s0, v90
	v_and_or_b32 v82, s21, 63, v2
	v_ashrrev_i32_e32 v83, 31, v82
	v_lshl_add_u64 v[2:3], v[76:77], 0, s[6:7]
	v_lshlrev_b64 v[4:5], 7, v[82:83]
	v_lshl_add_u64 v[4:5], v[2:3], 0, v[4:5]
	s_waitcnt lgkmcnt(0)
	s_barrier
	v_mov_b32_e32 v70, v120
	v_mov_b32_e32 v71, v121
	v_mov_b32_e32 v72, v122
	v_mov_b32_e32 v73, v123
	v_mov_b32_e32 v58, v124
	v_mov_b32_e32 v59, v125
	v_mov_b32_e32 v60, v126
	v_mov_b32_e32 v61, v127
	v_mov_b32_e32 v42, v128
	v_mov_b32_e32 v43, v129
	v_mov_b32_e32 v44, v130
	v_mov_b32_e32 v45, v131
	v_mov_b32_e32 v34, v132
	v_mov_b32_e32 v35, v133
	v_mov_b32_e32 v36, v134
	v_mov_b32_e32 v37, v135
	v_or_b32_e32 v84, 0x400, v82
	v_ashrrev_i32_e32 v85, 31, v84
	s_add_i32 s0, s11, s3
	v_lshlrev_b64 v[4:5], 7, v[84:85]
	v_or_b32_e32 v80, 0x800, v82
	s_cmpk_lt_i32 s0, 0x800
	v_lshl_add_u64 v[4:5], v[2:3], 0, v[4:5]
	v_ashrrev_i32_e32 v81, 31, v80
	s_cselect_b64 s[6:7], -1, 0
	v_lshlrev_b64 v[4:5], 7, v[80:81]
	v_or_b32_e32 v78, 0xc00, v82
	s_and_b64 s[22:23], s[6:7], exec
	v_lshl_add_u64 v[4:5], v[2:3], 0, v[4:5]
	v_ashrrev_i32_e32 v79, 31, v78
	s_cselect_b32 s11, s0, s11
	s_and_b32 s80, s11, 1
	s_lshl_b32 s80, s80, 2
	s_add_i32 s80, s8, s80
	s_mov_b32 s81, 0
	s_lshl_b64 s[80:81], s[80:81], 23
	s_lshl_b32 s82, s11, 5
	s_and_b32 s82, s82, 0xfffff000
	s_lshr_b32 s83, s11, 1
	s_and_b32 s83, s83, 63
	s_or_b32 s82, s82, s83
	v_or_b32_e32 v116, s82, v90
	v_lshlrev_b32_e32 v116, 7, v116
	v_mov_b32_e32 v117, 0
	v_lshl_add_u64 v[116:117], v[76:77], 0, v[116:117]
	v_lshl_add_u64 v[116:117], v[116:117], 0, s[80:81]
	global_load_dwordx4 v[120:123], v[116:117], off
	v_lshl_add_u64 v[116:117], v[116:117], 0, s[84:85]
	global_load_dwordx4 v[124:127], v[116:117], off
	v_lshl_add_u64 v[116:117], v[116:117], 0, s[84:85]
	global_load_dwordx4 v[128:131], v[116:117], off
	v_lshl_add_u64 v[116:117], v[116:117], 0, s[84:85]
	global_load_dwordx4 v[132:135], v[116:117], off
	v_lshlrev_b64 v[4:5], 7, v[78:79]
	s_lshl_b32 s21, s11, 5
	v_lshl_add_u64 v[2:3], v[2:3], 0, v[4:5]
	s_andn2_b32 s21, s21, 63
	v_or_b32_e32 v2, s21, v1
	v_ashrrev_i32_e32 v3, 31, v2
	s_lshl_b32 s11, s11, 8
	v_lshlrev_b64 v[2:3], 9, v[2:3]
	s_and_b32 s11, s11, 0x100
	v_or_b32_e32 v2, s11, v2
	v_or_b32_e32 v2, v2, v74
	v_lshlrev_b64 v[2:3], 1, v[2:3]
	v_lshl_add_u64 v[38:39], s[14:15], 0, v[2:3]
	v_lshl_add_u64 v[40:41], s[12:13], 0, v[2:3]
	global_load_dwordx4 v[2:5], v[38:39], off offset:384
	global_load_dwordx4 v[6:9], v[38:39], off offset:256
	global_load_dwordx4 v[10:13], v[38:39], off offset:128
	global_load_dwordx4 v[14:17], v[38:39], off
	global_load_dwordx4 v[18:21], v[40:41], off offset:384
	global_load_dwordx4 v[22:25], v[40:41], off offset:256
	global_load_dwordx4 v[26:29], v[40:41], off offset:128
	global_load_dwordx4 v[30:33], v[40:41], off
	ds_read_b64_tr_b16 v[40:41], v93 offset:2112
	ds_read_b64_tr_b16 v[38:39], v93
	ds_read_b64_tr_b16 v[46:47], v93 offset:8
	ds_read_b64_tr_b16 v[48:49], v93 offset:2120
	ds_read_b128 v[50:53], v94
	ds_read_b128 v[62:65], v94 offset:4352
	ds_read_b128 v[86:89], v94 offset:8704
	ds_read_b128 v[100:103], v94 offset:13056
	s_waitcnt lgkmcnt(3)
	v_mfma_f32_16x16x32_bf16 v[54:57], v[38:41], v[50:53], 0
	v_lshlrev_b64 v[82:83], 11, v[82:83]
	s_add_i32 s10, s10, s9
	s_mov_b32 s11, s0
	v_mfma_f32_16x16x32_bf16 v[50:53], v[46:49], v[50:53], 0
	v_lshlrev_b32_e32 v95, 16, v70
	s_waitcnt lgkmcnt(2)
	v_mfma_f32_16x16x32_bf16 v[66:69], v[38:41], v[62:65], 0
	v_and_b32_e32 v70, 0xffff0000, v70
	v_mfma_f32_16x16x32_bf16 v[62:65], v[46:49], v[62:65], 0
	s_waitcnt lgkmcnt(1)
	v_mfma_f32_16x16x32_bf16 v[96:99], v[38:41], v[86:89], 0
	v_mfma_f32_16x16x32_bf16 v[86:89], v[46:49], v[86:89], 0
	s_waitcnt lgkmcnt(0)
	v_mfma_f32_16x16x32_bf16 v[38:41], v[38:41], v[100:103], 0
	v_mfma_f32_16x16x32_bf16 v[46:49], v[46:49], v[100:103], 0
	ds_read_b64_tr_b16 v[100:101], v93 offset:16896
	ds_read_b64_tr_b16 v[102:103], v93 offset:19008
	ds_read_b64_tr_b16 v[104:105], v93 offset:16904
	ds_read_b64_tr_b16 v[106:107], v93 offset:19016
	ds_read_b128 v[108:111], v94 offset:64
	s_waitcnt lgkmcnt(0)
	v_mfma_f32_16x16x32_bf16 v[54:57], v[100:103], v[108:111], v[54:57]
	v_mfma_f32_16x16x32_bf16 v[50:53], v[104:107], v[108:111], v[50:53]
	ds_read_b128 v[108:111], v94 offset:4416
	s_waitcnt lgkmcnt(0)
	v_mfma_f32_16x16x32_bf16 v[66:69], v[100:103], v[108:111], v[66:69]
	v_mfma_f32_16x16x32_bf16 v[62:65], v[104:107], v[108:111], v[62:65]
	ds_read_b128 v[108:111], v94 offset:8768
	s_waitcnt lgkmcnt(0)
	v_mfma_f32_16x16x32_bf16 v[96:99], v[100:103], v[108:111], v[96:99]
	v_mfma_f32_16x16x32_bf16 v[86:89], v[104:107], v[108:111], v[86:89]
	ds_read_b128 v[108:111], v94 offset:13120
	s_waitcnt lgkmcnt(0)
	v_mfma_f32_16x16x32_bf16 v[38:41], v[100:103], v[108:111], v[38:41]
	v_mfma_f32_16x16x32_bf16 v[46:49], v[104:107], v[108:111], v[46:49]
	ds_read_b64_tr_b16 v[100:101], v93 offset:33792
	ds_read_b64_tr_b16 v[102:103], v93 offset:35904
	ds_read_b64_tr_b16 v[104:105], v93 offset:33800
	ds_read_b64_tr_b16 v[106:107], v93 offset:35912
	ds_read_b128 v[108:111], v94 offset:128
	s_waitcnt lgkmcnt(0)
	v_mfma_f32_16x16x32_bf16 v[54:57], v[100:103], v[108:111], v[54:57]
	v_mfma_f32_16x16x32_bf16 v[50:53], v[104:107], v[108:111], v[50:53]
	ds_read_b128 v[108:111], v94 offset:4480
	s_waitcnt lgkmcnt(0)
	v_mfma_f32_16x16x32_bf16 v[66:69], v[100:103], v[108:111], v[66:69]
	v_mfma_f32_16x16x32_bf16 v[62:65], v[104:107], v[108:111], v[62:65]
	ds_read_b128 v[108:111], v94 offset:8832
	s_waitcnt lgkmcnt(0)
	v_mfma_f32_16x16x32_bf16 v[96:99], v[100:103], v[108:111], v[96:99]
	v_mfma_f32_16x16x32_bf16 v[86:89], v[104:107], v[108:111], v[86:89]
	ds_read_b128 v[108:111], v94 offset:13184
	s_waitcnt lgkmcnt(0)
	v_mfma_f32_16x16x32_bf16 v[38:41], v[100:103], v[108:111], v[38:41]
	v_mfma_f32_16x16x32_bf16 v[100:103], v[104:107], v[108:111], v[46:49]
	s_nop 2
	ds_read_b64_tr_b16 v[46:47], v93 offset:50688
	ds_read_b64_tr_b16 v[48:49], v93 offset:52800
	ds_read_b64_tr_b16 v[104:105], v93 offset:50696
	ds_read_b64_tr_b16 v[106:107], v93 offset:52808
	ds_read_b128 v[108:111], v94 offset:192
	s_waitcnt lgkmcnt(0)
	v_mfma_f32_16x16x32_bf16 v[112:115], v[46:49], v[108:111], v[54:57]
	v_mfma_f32_16x16x32_bf16 v[108:111], v[104:107], v[108:111], v[50:53]
	s_nop 2
	ds_read_b128 v[50:53], v94 offset:4544
	s_waitcnt lgkmcnt(0)
	v_mfma_f32_16x16x32_bf16 v[66:69], v[46:49], v[50:53], v[66:69]
	v_mfma_f32_16x16x32_bf16 v[62:65], v[104:107], v[50:53], v[62:65]
	ds_read_b128 v[50:53], v94 offset:8896
	s_nop 5
	v_pk_mul_f32 v[66:67], v[66:67], s[4:5] op_sel_hi:[1,0]
	v_pk_mul_f32 v[68:69], v[68:69], s[4:5] op_sel_hi:[1,0]
	s_waitcnt lgkmcnt(0)
	v_mfma_f32_16x16x32_bf16 v[54:57], v[46:49], v[50:53], v[96:99]
	s_nop 2
	v_mul_f32_e32 v98, 0xbfb8aa3b, v95
	v_mul_f32_e32 v99, 0xbfb8aa3b, v70
	v_mfma_f32_16x16x32_bf16 v[50:53], v[104:107], v[50:53], v[86:89]
	v_exp_f32_e32 v98, v98
	v_exp_f32_e32 v99, v99
	v_pk_mul_f32 v[96:97], v[112:113], s[4:5] op_sel_hi:[1,0]
	ds_read_b128 v[86:89], v94 offset:13248
	s_waitcnt lgkmcnt(0)
	v_mfma_f32_16x16x32_bf16 v[46:49], v[46:49], v[86:89], v[38:41]
	v_add_f32_e64 v98, v98, 1.0
	v_add_f32_e64 v99, v99, 1.0
	v_pk_mul_f32 v[62:63], v[62:63], s[4:5] op_sel_hi:[1,0]
	v_pk_mul_f32 v[64:65], v[64:65], s[4:5] op_sel_hi:[1,0]
	v_mfma_f32_16x16x32_bf16 v[38:41], v[104:107], v[86:89], v[100:103]
	v_lshl_add_u32 v86, s20, 8, v91
	v_pk_mul_f32 v[88:89], v[114:115], s[4:5] op_sel_hi:[1,0]
	v_ashrrev_i32_e32 v87, 31, v86
	v_pk_mul_f32 v[54:55], v[54:55], s[4:5] op_sel_hi:[1,0]
	v_pk_mul_f32 v[56:57], v[56:57], s[4:5] op_sel_hi:[1,0]
	v_pk_mul_f32 v[50:51], v[50:51], s[4:5] op_sel_hi:[1,0]
	v_rcp_f32_e32 v100, v99
	s_nop 0
	v_mul_f32_e32 v99, v70, v100
	v_pk_mul_f32 v[52:53], v[52:53], s[4:5] op_sel_hi:[1,0]
	s_nop 1
	v_pk_mul_f32 v[38:39], v[38:39], s[4:5] op_sel_hi:[1,0]
	v_pk_mul_f32 v[40:41], v[40:41], s[4:5] op_sel_hi:[1,0]
	v_rcp_f32_e32 v70, v98
	s_nop 0
	v_mul_f32_e32 v98, v95, v70
	v_pk_mul_f32 v[96:97], v[98:99], v[96:97]
	v_lshlrev_b32_e32 v95, 16, v71
	v_and_b32_e32 v71, 0xffff0000, v71
	v_cvt_pk_bf16_f32 v70, v96, v97
	v_mul_f32_e32 v96, 0xbfb8aa3b, v95
	v_mul_f32_e32 v97, 0xbfb8aa3b, v71
	v_exp_f32_e32 v96, v96
	v_exp_f32_e32 v97, v97
	s_nop 0
	v_pk_add_f32 v[96:97], v[96:97], 1.0 op_sel_hi:[1,0]
	s_nop 0
	s_nop 0
	v_rcp_f32_e32 v98, v97
	s_nop 0
	v_mul_f32_e32 v97, v71, v98
	s_nop 0
	v_rcp_f32_e32 v71, v96
	s_nop 0
	v_mul_f32_e32 v96, v95, v71
	v_lshlrev_b32_e32 v95, 16, v72
	v_and_b32_e32 v72, 0xffff0000, v72
	v_mul_f32_e32 v98, 0xbfb8aa3b, v95
	v_mul_f32_e32 v99, 0xbfb8aa3b, v72
	v_exp_f32_e32 v98, v98
	v_exp_f32_e32 v99, v99
	v_pk_mul_f32 v[88:89], v[96:97], v[88:89]
	v_pk_mul_f32 v[96:97], v[108:109], s[4:5] op_sel_hi:[1,0]
	v_cvt_pk_bf16_f32 v71, v88, v89
	v_pk_add_f32 v[98:99], v[98:99], 1.0 op_sel_hi:[1,0]
	v_pk_mul_f32 v[88:89], v[110:111], s[4:5] op_sel_hi:[1,0]
	s_nop 0
	v_rcp_f32_e32 v100, v99
	s_nop 0
	v_mul_f32_e32 v99, v72, v100
	s_nop 0
	v_rcp_f32_e32 v72, v98
	s_nop 0
	v_mul_f32_e32 v98, v95, v72
	v_pk_mul_f32 v[96:97], v[98:99], v[96:97]
	v_lshlrev_b32_e32 v95, 16, v73
	v_and_b32_e32 v73, 0xffff0000, v73
	v_cvt_pk_bf16_f32 v72, v96, v97
	v_mul_f32_e32 v96, 0xbfb8aa3b, v95
	v_mul_f32_e32 v97, 0xbfb8aa3b, v73
	v_exp_f32_e32 v96, v96
	v_exp_f32_e32 v97, v97
	s_nop 0
	v_pk_add_f32 v[96:97], v[96:97], 1.0 op_sel_hi:[1,0]
	s_nop 0
	s_nop 0
	v_rcp_f32_e32 v98, v97
	s_nop 0
	v_mul_f32_e32 v97, v73, v98
	s_nop 0
	v_rcp_f32_e32 v73, v96
	s_nop 0
	v_mul_f32_e32 v96, v95, v73
	v_pk_mul_f32 v[88:89], v[96:97], v[88:89]
	s_nop 0
	v_cvt_pk_bf16_f32 v73, v88, v89
	v_lshl_add_u64 v[88:89], s[18:19], 0, v[82:83]
	v_lshlrev_b64 v[82:83], 1, v[86:87]
	v_lshl_add_u64 v[86:87], v[88:89], 0, v[82:83]
	global_store_dwordx4 v[86:87], v[70:73], off offset:1024
	s_nop 0
	s_nop 0
	v_lshlrev_b32_e32 v72, 16, v58
	v_and_b32_e32 v58, 0xffff0000, v58
	v_mul_f32_e32 v70, 0xbfb8aa3b, v72
	v_mul_f32_e32 v71, 0xbfb8aa3b, v58
	v_exp_f32_e32 v70, v70
	v_exp_f32_e32 v71, v71
	s_nop 0
	v_pk_add_f32 v[70:71], v[70:71], 1.0 op_sel_hi:[1,0]
	s_nop 0
	s_nop 0
	v_rcp_f32_e32 v73, v71
	s_nop 0
	v_mul_f32_e32 v71, v58, v73
	s_nop 0
	v_rcp_f32_e32 v58, v70
	s_nop 0
	v_mul_f32_e32 v70, v72, v58
	v_pk_mul_f32 v[66:67], v[70:71], v[66:67]
	v_lshlrev_b32_e32 v70, 16, v59
	v_and_b32_e32 v59, 0xffff0000, v59
	v_cvt_pk_bf16_f32 v58, v66, v67
	v_mul_f32_e32 v66, 0xbfb8aa3b, v70
	v_mul_f32_e32 v67, 0xbfb8aa3b, v59
	v_exp_f32_e32 v66, v66
	v_exp_f32_e32 v67, v67
	s_nop 0
	v_pk_add_f32 v[66:67], v[66:67], 1.0 op_sel_hi:[1,0]
	s_nop 0
	s_nop 0
	v_rcp_f32_e32 v71, v67
	s_nop 0
	v_mul_f32_e32 v67, v59, v71
	s_nop 0
	v_rcp_f32_e32 v59, v66
	s_nop 0
	v_mul_f32_e32 v66, v70, v59
	v_pk_mul_f32 v[66:67], v[66:67], v[68:69]
	v_lshlrev_b32_e32 v68, 16, v60
	v_and_b32_e32 v60, 0xffff0000, v60
	v_cvt_pk_bf16_f32 v59, v66, v67
	v_mul_f32_e32 v66, 0xbfb8aa3b, v68
	v_mul_f32_e32 v67, 0xbfb8aa3b, v60
	v_exp_f32_e32 v66, v66
	v_exp_f32_e32 v67, v67
	s_nop 0
	v_pk_add_f32 v[66:67], v[66:67], 1.0 op_sel_hi:[1,0]
	s_nop 0
	s_nop 0
	v_rcp_f32_e32 v69, v67
	s_nop 0
	v_mul_f32_e32 v67, v60, v69
	s_nop 0
	v_rcp_f32_e32 v60, v66
	s_nop 0
	v_mul_f32_e32 v66, v68, v60
	v_pk_mul_f32 v[62:63], v[66:67], v[62:63]
	v_lshlrev_b32_e32 v66, 16, v61
	v_and_b32_e32 v61, 0xffff0000, v61
	v_cvt_pk_bf16_f32 v60, v62, v63
	v_mul_f32_e32 v62, 0xbfb8aa3b, v66
	v_mul_f32_e32 v63, 0xbfb8aa3b, v61
	v_exp_f32_e32 v62, v62
	v_exp_f32_e32 v63, v63
	s_nop 0
	v_pk_add_f32 v[62:63], v[62:63], 1.0 op_sel_hi:[1,0]
	s_nop 0
	s_nop 0
	v_rcp_f32_e32 v67, v63
	s_nop 0
	v_mul_f32_e32 v63, v61, v67
	s_nop 0
	v_rcp_f32_e32 v61, v62
	s_nop 0
	v_mul_f32_e32 v62, v66, v61
	v_pk_mul_f32 v[62:63], v[62:63], v[64:65]
	s_nop 0
	v_cvt_pk_bf16_f32 v61, v62, v63
	v_lshlrev_b64 v[62:63], 11, v[84:85]
	v_lshl_add_u64 v[62:63], s[18:19], 0, v[62:63]
	v_lshl_add_u64 v[62:63], v[62:63], 0, v[82:83]
	global_store_dwordx4 v[62:63], v[58:61], off offset:1024
	s_nop 0
	s_nop 0
	v_lshlrev_b32_e32 v60, 16, v42
	v_and_b32_e32 v42, 0xffff0000, v42
	v_mul_f32_e32 v58, 0xbfb8aa3b, v60
	v_mul_f32_e32 v59, 0xbfb8aa3b, v42
	v_exp_f32_e32 v58, v58
	v_exp_f32_e32 v59, v59
	s_nop 0
	v_pk_add_f32 v[58:59], v[58:59], 1.0 op_sel_hi:[1,0]
	s_nop 0
	s_nop 0
	v_rcp_f32_e32 v61, v59
	s_nop 0
	v_mul_f32_e32 v59, v42, v61
	s_nop 0
	v_rcp_f32_e32 v42, v58
	s_nop 0
	v_mul_f32_e32 v58, v60, v42
	v_pk_mul_f32 v[54:55], v[58:59], v[54:55]
	v_lshlrev_b32_e32 v58, 16, v43
	v_and_b32_e32 v43, 0xffff0000, v43
	v_cvt_pk_bf16_f32 v42, v54, v55
	v_mul_f32_e32 v54, 0xbfb8aa3b, v58
	v_mul_f32_e32 v55, 0xbfb8aa3b, v43
	v_exp_f32_e32 v54, v54
	v_exp_f32_e32 v55, v55
	s_nop 0
	v_pk_add_f32 v[54:55], v[54:55], 1.0 op_sel_hi:[1,0]
	s_nop 0
	s_nop 0
	v_rcp_f32_e32 v59, v55
	s_nop 0
	v_mul_f32_e32 v55, v43, v59
	s_nop 0
	v_rcp_f32_e32 v43, v54
	s_nop 0
	v_mul_f32_e32 v54, v58, v43
	v_pk_mul_f32 v[54:55], v[54:55], v[56:57]
	v_lshlrev_b32_e32 v56, 16, v44
	v_and_b32_e32 v44, 0xffff0000, v44
	v_cvt_pk_bf16_f32 v43, v54, v55
	v_mul_f32_e32 v54, 0xbfb8aa3b, v56
	v_mul_f32_e32 v55, 0xbfb8aa3b, v44
	v_exp_f32_e32 v54, v54
	v_exp_f32_e32 v55, v55
	s_nop 0
	v_pk_add_f32 v[54:55], v[54:55], 1.0 op_sel_hi:[1,0]
	s_nop 0
	s_nop 0
	v_rcp_f32_e32 v57, v55
	s_nop 0
	v_mul_f32_e32 v55, v44, v57
	s_nop 0
	v_rcp_f32_e32 v44, v54
	s_nop 0
	v_mul_f32_e32 v54, v56, v44
	v_pk_mul_f32 v[50:51], v[54:55], v[50:51]
	v_lshlrev_b32_e32 v54, 16, v45
	v_and_b32_e32 v45, 0xffff0000, v45
	v_cvt_pk_bf16_f32 v44, v50, v51
	v_mul_f32_e32 v50, 0xbfb8aa3b, v54
	v_mul_f32_e32 v51, 0xbfb8aa3b, v45
	v_exp_f32_e32 v50, v50
	v_exp_f32_e32 v51, v51
	s_nop 0
	v_pk_add_f32 v[50:51], v[50:51], 1.0 op_sel_hi:[1,0]
	s_nop 0
	s_nop 0
	v_rcp_f32_e32 v55, v51
	s_nop 0
	v_mul_f32_e32 v51, v45, v55
	s_nop 0
	v_rcp_f32_e32 v45, v50
	s_nop 0
	v_mul_f32_e32 v50, v54, v45
	v_pk_mul_f32 v[50:51], v[50:51], v[52:53]
	s_nop 0
	v_cvt_pk_bf16_f32 v45, v50, v51
	v_lshlrev_b64 v[50:51], 11, v[80:81]
	v_lshl_add_u64 v[50:51], s[18:19], 0, v[50:51]
	v_lshl_add_u64 v[50:51], v[50:51], 0, v[82:83]
	global_store_dwordx4 v[50:51], v[42:45], off offset:1024
	s_nop 1
	v_pk_mul_f32 v[42:43], v[48:49], s[4:5] op_sel_hi:[1,0]
	v_lshlrev_b32_e32 v48, 16, v34
	v_and_b32_e32 v34, 0xffff0000, v34
	v_pk_mul_f32 v[44:45], v[46:47], s[4:5] op_sel_hi:[1,0]
	v_mul_f32_e32 v46, 0xbfb8aa3b, v48
	v_mul_f32_e32 v47, 0xbfb8aa3b, v34
	v_exp_f32_e32 v46, v46
	v_exp_f32_e32 v47, v47
	s_nop 0
	v_pk_add_f32 v[46:47], v[46:47], 1.0 op_sel_hi:[1,0]
	s_nop 0
	s_nop 0
	v_rcp_f32_e32 v49, v47
	s_nop 0
	v_mul_f32_e32 v47, v34, v49
	s_nop 0
	v_rcp_f32_e32 v34, v46
	s_nop 0
	v_mul_f32_e32 v46, v48, v34
	v_pk_mul_f32 v[44:45], v[46:47], v[44:45]
	v_lshlrev_b32_e32 v46, 16, v35
	v_and_b32_e32 v35, 0xffff0000, v35
	v_cvt_pk_bf16_f32 v34, v44, v45
	v_mul_f32_e32 v44, 0xbfb8aa3b, v46
	v_mul_f32_e32 v45, 0xbfb8aa3b, v35
	v_exp_f32_e32 v44, v44
	v_exp_f32_e32 v45, v45
	s_nop 0
	v_pk_add_f32 v[44:45], v[44:45], 1.0 op_sel_hi:[1,0]
	s_nop 0
	s_nop 0
	v_rcp_f32_e32 v47, v45
	s_nop 0
	v_mul_f32_e32 v45, v35, v47
	s_nop 0
	v_rcp_f32_e32 v35, v44
	s_nop 0
	v_mul_f32_e32 v44, v46, v35
	v_pk_mul_f32 v[42:43], v[44:45], v[42:43]
	v_lshlrev_b32_e32 v44, 16, v36
	v_and_b32_e32 v36, 0xffff0000, v36
	v_cvt_pk_bf16_f32 v35, v42, v43
	v_mul_f32_e32 v42, 0xbfb8aa3b, v44
	v_mul_f32_e32 v43, 0xbfb8aa3b, v36
	v_exp_f32_e32 v42, v42
	v_exp_f32_e32 v43, v43
	s_nop 0
	v_pk_add_f32 v[42:43], v[42:43], 1.0 op_sel_hi:[1,0]
	s_nop 0
	s_nop 0
	v_rcp_f32_e32 v45, v43
	s_nop 0
	v_mul_f32_e32 v43, v36, v45
	s_nop 0
	v_rcp_f32_e32 v36, v42
	s_nop 0
	v_mul_f32_e32 v42, v44, v36
	v_pk_mul_f32 v[38:39], v[42:43], v[38:39]
	v_lshlrev_b32_e32 v42, 16, v37
	v_and_b32_e32 v37, 0xffff0000, v37
	v_cvt_pk_bf16_f32 v36, v38, v39
	v_mul_f32_e32 v38, 0xbfb8aa3b, v42
	v_mul_f32_e32 v39, 0xbfb8aa3b, v37
	v_exp_f32_e32 v38, v38
	v_exp_f32_e32 v39, v39
	s_nop 0
	v_pk_add_f32 v[38:39], v[38:39], 1.0 op_sel_hi:[1,0]
	s_nop 0
	s_nop 0
	v_rcp_f32_e32 v43, v39
	s_nop 0
	v_mul_f32_e32 v39, v37, v43
	s_nop 0
	v_rcp_f32_e32 v37, v38
	s_nop 0
	v_mul_f32_e32 v38, v42, v37
	v_pk_mul_f32 v[38:39], v[38:39], v[40:41]
	s_and_b64 vcc, s[6:7], exec
	v_cvt_pk_bf16_f32 v37, v38, v39
	v_lshlrev_b64 v[38:39], 11, v[78:79]
	v_lshl_add_u64 v[38:39], s[18:19], 0, v[38:39]
	v_lshl_add_u64 v[38:39], v[38:39], 0, v[82:83]
	global_store_dwordx4 v[38:39], v[34:37], off offset:1024
	s_cbranch_vccnz .LBB0_308
